# P5 epilogue: second batch of 8 gate loads issued right after the staging barrier into freed accumulator registers, consumed after batch 1 (no vmcnt waits left in the epilogue compute)
# speedup vs baseline: 1.0317x; 1.0018x over previous
; DI void wait_vm0() { asm volatile("s_waitcnt vmcnt(0)" ::: "memory"); }
; DI void bar_() { __builtin_amdgcn_s_barrier(); }
; DI void lds_sync() { wait_lgkm0(); bar_(); }
; #define SB_ __builtin_amdgcn_sched_barrier(0)
; template <int TM, int TN, int WM, int WN, bool SUMSQ, int NST, class AF, class BF, class AFN, class BFN>
; DI void gemm8x(f32x16 (&acc)[TM][TN], AF arow, BF brow, int K, char* smem, float& sumsq, bool pre, bool hasNext, AFN arowN, BFN browN) {
;     ...
;   for (int kt = 0; kt < nk - 1; ++kt) {
;     SB_;
;     if (NST == 2) {
;       const int ko = (kt + 1) * 64;
;       compute(smem + (kt & 1) * STAGE, smem + ((kt + 1) & 1) * STAGE, true, pa0 + ko, pa1 + ko, pa2 + ko, pa3 + ko, pb0 + ko, pb1 + ko, pb2 + ko, pb3 + ko);
;       SB_;
;       wait_vm0(); bar_();
;     } else {
;       const int ko = (kt + 2) * 64; const bool iss = kt + 2 < nk;
;       const int sn = (sc_ == 0) ? 2 : sc_ - 1;
;       compute(smem + sc_ * STAGE, smem + sn * STAGE, iss, pa0 + ko, pa1 + ko, pa2 + ko, pa3 + ko, pb0 + ko, pb1 + ko, pb2 + ko, pb3 + ko);
;       SB_;
;       if (iss) asm volatile("s_waitcnt vmcnt(6)" ::: "memory"); else wait_vm0();
;       bar_();
;       sc_ = (sc_ == 2) ? 0 : sc_ + 1;
;     }
;   }
;   if (NST == 3) {
;     SB_;
;     compute(smem + sc_ * STAGE, smem, false, pa0, pa0, pa0, pa0, pa0, pa0, pa0, pa0);
;     SB_;
;     lds_sync();
; DI void phase5(const Params& p, char* smem) {
;     ...
;         uint4 gav[4], gbv[4];
; #pragma unroll
;         for (int i = 0; i < 4; ++i) {
;           const size_t tok = (size_t)tokTile * 128 + r0 + 16 * (hb * 4 + i);
;           gav[i] = *(const uint4*)(p.pg + tok * 2048 + nt * 256 + ch * 8); gbv[i] = *(const uint4*)(p.pg + tok * 2048 + 1024 + nt * 256 + ch * 8);
.LBB0_657:
	s_or_b64 exec, exec, s[4:5]
	s_lshl_b32 s26, s26, 7
	v_lshl_add_u64 v[218:219], s[26:27], 0, v[168:169]
	v_lshlrev_b64 v[218:219], 12, v[218:219]
	v_lshl_add_u64 v[218:219], s[24:25], 0, v[218:219]
	s_lshl_b32 s98, s61, 9
	s_mov_b32 s99, s27
	v_lshl_add_u64 v[218:219], v[218:219], 0, s[98:99]
	v_mov_b32_e32 v216, v186
	v_mov_b32_e32 v217, v171
	v_lshl_add_u64 v[218:219], v[218:219], 0, v[216:217]
	global_load_dwordx4 v[188:191], v[218:219], off
	global_load_dwordx4 v[192:195], v[218:219], off offset:2048
	s_mov_b32 s99, 0
	s_mov_b32 s98, s53
	v_lshl_add_u64 v[216:217], v[218:219], 0, s[98:99]
	global_load_dwordx4 v[196:199], v[216:217], off
	global_load_dwordx4 v[200:203], v[216:217], off offset:2048
	s_mov_b32 s98, s54
	v_lshl_add_u64 v[216:217], v[218:219], 0, s[98:99]
	global_load_dwordx4 v[234:237], v[216:217], off
	global_load_dwordx4 v[238:241], v[216:217], off offset:2048
	s_mov_b32 s98, s55
	v_lshl_add_u64 v[216:217], v[218:219], 0, s[98:99]
	global_load_dwordx4 v[242:245], v[216:217], off
	global_load_dwordx4 v[246:249], v[216:217], off offset:2048
	v_mfma_f32_32x32x16_bf16 v[112:127], v[160:163], v[164:167], v[112:127]
	v_mfma_f32_32x32x16_bf16 v[96:111], v[160:163], v[148:151], v[96:111]
	v_mfma_f32_32x32x16_bf16 v[80:95], v[144:147], v[164:167], v[80:95]
	v_mfma_f32_32x32x16_bf16 v[64:79], v[144:147], v[148:151], v[64:79]
	s_setprio 0
	s_waitcnt vmcnt(14)
	s_barrier
	ds_read_b128 v[128:131], v225
	ds_read_b128 v[132:135], v225 offset:4096
	ds_read_b128 v[136:139], v233 offset:32768
	ds_read_b128 v[140:143], v233 offset:36864
	ds_read_b128 v[144:147], v227
	ds_read_b128 v[148:151], v227 offset:4096
	ds_read_b128 v[152:155], v232 offset:32768
	ds_read_b128 v[156:159], v232 offset:36864
	s_setprio 1
	s_waitcnt lgkmcnt(0)
	v_mfma_f32_32x32x16_bf16 v[112:127], v[128:131], v[136:139], v[112:127]
	v_mfma_f32_32x32x16_bf16 v[96:111], v[128:131], v[140:143], v[96:111]
	v_mfma_f32_32x32x16_bf16 v[80:95], v[132:135], v[136:139], v[80:95]
	ds_read_b128 v[128:131], v170
	ds_read_b128 v[136:139], v170 offset:4096
	ds_read_b128 v[160:163], v208 offset:32768
	ds_read_b128 v[164:167], v208 offset:36864
	v_mfma_f32_32x32x16_bf16 v[64:79], v[132:135], v[140:143], v[64:79]
	v_mfma_f32_32x32x16_bf16 v[112:127], v[144:147], v[152:155], v[112:127]
	v_mfma_f32_32x32x16_bf16 v[96:111], v[144:147], v[156:159], v[96:111]
	v_mfma_f32_32x32x16_bf16 v[80:95], v[148:151], v[152:155], v[80:95]
	ds_read_b128 v[132:135], v187
	ds_read_b128 v[140:143], v187 offset:4096
	ds_read_b128 v[144:147], v213 offset:32768
	ds_read_b128 v[152:155], v213 offset:36864
	v_mfma_f32_32x32x16_bf16 v[64:79], v[148:151], v[156:159], v[64:79]
	s_waitcnt lgkmcnt(0)
	v_mfma_f32_32x32x16_bf16 v[112:127], v[128:131], v[160:163], v[112:127]
	v_mfma_f32_32x32x16_bf16 v[96:111], v[128:131], v[164:167], v[96:111]
	v_mfma_f32_32x32x16_bf16 v[80:95], v[136:139], v[160:163], v[80:95]
	v_mfma_f32_32x32x16_bf16 v[64:79], v[136:139], v[164:167], v[64:79]
	v_mfma_f32_32x32x16_bf16 v[112:127], v[132:135], v[144:147], v[112:127]
	v_mfma_f32_32x32x16_bf16 v[96:111], v[132:135], v[152:155], v[96:111]
	v_mfma_f32_32x32x16_bf16 v[80:95], v[140:143], v[144:147], v[80:95]
	v_mfma_f32_32x32x16_bf16 v[64:79], v[140:143], v[152:155], v[64:79]
	s_setprio 0
	s_waitcnt vmcnt(8)
	s_barrier
	ds_read_b128 v[128:131], v225 offset:49152
	ds_read_b128 v[132:135], v225 offset:53248
	ds_read_b128 v[136:139], v226
	ds_read_b128 v[140:143], v226 offset:4096
	ds_read_b128 v[144:147], v227 offset:49152
	ds_read_b128 v[148:151], v227 offset:53248
	ds_read_b128 v[152:155], v228
	ds_read_b128 v[156:159], v228 offset:4096
	s_setprio 1
	s_waitcnt lgkmcnt(0)
	v_mfma_f32_32x32x16_bf16 v[112:127], v[128:131], v[136:139], v[112:127]
	v_mfma_f32_32x32x16_bf16 v[96:111], v[128:131], v[140:143], v[96:111]
	v_mfma_f32_32x32x16_bf16 v[80:95], v[132:135], v[136:139], v[80:95]
	ds_read_b128 v[128:131], v170 offset:49152
	ds_read_b128 v[136:139], v170 offset:53248
	ds_read_b128 v[160:163], v229
	ds_read_b128 v[164:167], v229 offset:4096
	v_mfma_f32_32x32x16_bf16 v[64:79], v[132:135], v[140:143], v[64:79]
	v_mfma_f32_32x32x16_bf16 v[112:127], v[144:147], v[152:155], v[112:127]
	v_mfma_f32_32x32x16_bf16 v[96:111], v[144:147], v[156:159], v[96:111]
	v_mfma_f32_32x32x16_bf16 v[80:95], v[148:151], v[152:155], v[80:95]
	ds_read_b128 v[132:135], v187 offset:49152
	ds_read_b128 v[140:143], v187 offset:53248
	ds_read_b128 v[144:147], v230
	ds_read_b128 v[152:155], v230 offset:4096
	v_mfma_f32_32x32x16_bf16 v[64:79], v[148:151], v[156:159], v[64:79]
	s_waitcnt lgkmcnt(0)
	v_mfma_f32_32x32x16_bf16 v[112:127], v[128:131], v[160:163], v[112:127]
	v_mfma_f32_32x32x16_bf16 v[96:111], v[128:131], v[164:167], v[96:111]
	v_mfma_f32_32x32x16_bf16 v[80:95], v[136:139], v[160:163], v[80:95]
	v_mfma_f32_32x32x16_bf16 v[64:79], v[136:139], v[164:167], v[64:79]
	v_mfma_f32_32x32x16_bf16 v[112:127], v[132:135], v[144:147], v[112:127]
	v_mfma_f32_32x32x16_bf16 v[96:111], v[132:135], v[152:155], v[96:111]
	v_mfma_f32_32x32x16_bf16 v[80:95], v[140:143], v[144:147], v[80:95]
	v_mfma_f32_32x32x16_bf16 v[64:79], v[140:143], v[152:155], v[64:79]
	s_setprio 0
	v_mov_b32_e32 v128, v220
	s_waitcnt lgkmcnt(0)
	s_barrier
; DI unsigned pk_bf16(float lo, float hi) { f32x2v v = {lo, hi}; bf16x2v b = __builtin_convertvector(v, bf16x2v); return __builtin_bit_cast(unsigned, b); }
; DI int tid_() { int t = threadIdx.x; asm volatile("" : "+v"(t)); return t; }
; DI void lds_sync() { wait_lgkm0(); bar_(); }
; template <int TM, int TN, int WM, int WN, class F>
; DI void stage_tile(const f32x16 (&acc)[TM][TN], char* tile, int pitch, F f) {
;   const int t = tid_(), lane = t & 63, w = t >> 6, r = lane & 31, hh = lane >> 5;
;   const int wm = w % WM, wn = w / WM;
; #pragma unroll
;   for (int tm = 0; tm < TM; ++tm)
; #pragma unroll
;     for (int tn = 0; tn < TN; ++tn) {
;       char* d = tile + (wn * TN * 32 + tn * 32 + r) * pitch + (wm * TM * 32 + tm * 32 + 4 * hh) * 2;
; #pragma unroll
;       for (int q = 0; q < 4; ++q) {
;         uint2 o; o.x = pk_bf16(f(acc[tm][tn][4 * q]), f(acc[tm][tn][4 * q + 1])); o.y = pk_bf16(f(acc[tm][tn][4 * q + 2]), f(acc[tm][tn][4 * q + 3]));
;         *(uint2*)(d + 16 * q) = o;
;       }
;     }
; }
; DI void phase5(const Params& p, char* smem) {
;     ...
;     {
;       char* t1 = smem; char* t2 = smem + 128 * 528;
;       const int ch = t & 31, r0 = t >> 5;
;       stage_tile<2, 2, 4, 2>(acc1, t1, 528, [](float v) { return v; });
;       stage_tile<2, 2, 4, 2>(acc2, t2, 528, [](float v) { return v; });
;       lds_sync();
	v_cvt_pk_bf16_f32 v32, v32, v33
	v_ashrrev_i32_e32 v129, 6, v128
	v_lshrrev_b32_e32 v131, 30, v129
	v_add_u32_e32 v131, v129, v131
	v_ashrrev_i32_e32 v131, 2, v131
	v_and_b32_e32 v130, 31, v128
	v_mul_i32_i24_e32 v132, 4, v131
	v_lshrrev_b32_e32 v128, 2, v128
	v_sub_u32_e32 v129, v129, v132
	v_and_b32_e32 v128, 8, v128
	v_lshl_or_b32 v130, v131, 6, v130
	v_lshl_or_b32 v128, v129, 7, v128
	v_mad_u64_u32 v[128:129], s[4:5], v130, s47, v[128:129]
	v_cvt_pk_bf16_f32 v33, v34, v35
	v_cvt_pk_bf16_f32 v34, v36, v37
	v_add_u32_e32 v36, 0x4000, v128
	v_cvt_pk_bf16_f32 v0, v0, v1
	v_cvt_pk_bf16_f32 v1, v2, v3
	v_cvt_pk_bf16_f32 v2, v4, v5
	v_cvt_pk_bf16_f32 v3, v6, v7
	v_cvt_pk_bf16_f32 v48, v48, v49
	v_cvt_pk_bf16_f32 v49, v50, v51
	v_cvt_pk_bf16_f32 v50, v52, v53
	v_cvt_pk_bf16_f32 v51, v54, v55
	v_cvt_pk_bf16_f32 v35, v38, v39
	v_cvt_pk_bf16_f32 v16, v16, v17
	v_cvt_pk_bf16_f32 v17, v18, v19
	v_cvt_pk_bf16_f32 v18, v20, v21
	v_cvt_pk_bf16_f32 v19, v22, v23
	s_waitcnt vmcnt(8)
	ds_write2_b64 v36, v[0:1], v[2:3] offset0:72 offset1:74
	v_cvt_pk_bf16_f32 v0, v8, v9
	v_cvt_pk_bf16_f32 v1, v10, v11
	v_cvt_pk_bf16_f32 v2, v12, v13
	v_cvt_pk_bf16_f32 v3, v14, v15
	ds_write2_b64 v128, v[48:49], v[50:51] offset1:2
	v_cvt_pk_bf16_f32 v48, v56, v57
	v_cvt_pk_bf16_f32 v49, v58, v59
	v_cvt_pk_bf16_f32 v50, v60, v61
	v_cvt_pk_bf16_f32 v51, v62, v63
	ds_write2_b64 v36, v[32:33], v[34:35] offset0:64 offset1:66
	v_cvt_pk_bf16_f32 v32, v40, v41
	v_cvt_pk_bf16_f32 v33, v42, v43
	v_cvt_pk_bf16_f32 v34, v44, v45
	v_cvt_pk_bf16_f32 v35, v46, v47
	ds_write2_b64 v128, v[16:17], v[18:19] offset0:8 offset1:10
	v_cvt_pk_bf16_f32 v16, v24, v25
	v_cvt_pk_bf16_f32 v17, v26, v27
	v_cvt_pk_bf16_f32 v18, v28, v29
	v_cvt_pk_bf16_f32 v19, v30, v31
	ds_write2_b64 v36, v[0:1], v[2:3] offset0:76 offset1:78
	v_mov_b32_e32 v0, v220
	ds_write2_b64 v128, v[48:49], v[50:51] offset0:4 offset1:6
	ds_write2_b64 v36, v[32:33], v[34:35] offset0:68 offset1:70
	ds_write2_b64 v128, v[16:17], v[18:19] offset0:12 offset1:14
	v_cvt_pk_bf16_f32 v5, v118, v119
	v_ashrrev_i32_e32 v1, 6, v0
	v_lshrrev_b32_e32 v3, 30, v1
	v_add_u32_e32 v3, v1, v3
	v_ashrrev_i32_e32 v3, 2, v3
	v_and_b32_e32 v2, 31, v0
	v_mul_i32_i24_e32 v4, 4, v3
	v_lshrrev_b32_e32 v0, 2, v0
	v_sub_u32_e32 v1, v1, v4
	v_and_b32_e32 v0, 8, v0
	v_lshl_or_b32 v2, v3, 6, v2
	v_lshl_or_b32 v0, v1, 7, v0
	v_mad_u64_u32 v[0:1], s[4:5], v2, s47, v[0:1]
	v_add_u32_e32 v1, 0x10800, v0
	v_cvt_pk_bf16_f32 v2, v112, v113
	v_cvt_pk_bf16_f32 v3, v114, v115
	v_cvt_pk_bf16_f32 v4, v116, v117
	ds_write2_b64 v1, v[2:3], v[4:5] offset1:2
	v_cvt_pk_bf16_f32 v2, v120, v121
	v_cvt_pk_bf16_f32 v3, v122, v123
	v_cvt_pk_bf16_f32 v4, v124, v125
	v_cvt_pk_bf16_f32 v5, v126, v127
	ds_write2_b64 v1, v[2:3], v[4:5] offset0:4 offset1:6
	v_cvt_pk_bf16_f32 v2, v96, v97
	v_cvt_pk_bf16_f32 v3, v98, v99
	v_cvt_pk_bf16_f32 v4, v100, v101
	v_cvt_pk_bf16_f32 v5, v102, v103
	v_add_u32_e32 v1, 0x4000, v1
	ds_write2_b64 v1, v[2:3], v[4:5] offset0:64 offset1:66
	v_cvt_pk_bf16_f32 v2, v104, v105
	v_cvt_pk_bf16_f32 v3, v106, v107
	v_cvt_pk_bf16_f32 v4, v108, v109
	v_cvt_pk_bf16_f32 v5, v110, v111
	ds_write2_b64 v1, v[2:3], v[4:5] offset0:68 offset1:70
	v_add_u32_e32 v4, 0x10840, v0
	v_cvt_pk_bf16_f32 v0, v80, v81
	v_cvt_pk_bf16_f32 v1, v82, v83
	v_cvt_pk_bf16_f32 v2, v84, v85
	v_cvt_pk_bf16_f32 v3, v86, v87
	ds_write2_b64 v4, v[0:1], v[2:3] offset1:2
	v_cvt_pk_bf16_f32 v0, v88, v89
	v_cvt_pk_bf16_f32 v1, v90, v91
	v_cvt_pk_bf16_f32 v2, v92, v93
	v_cvt_pk_bf16_f32 v3, v94, v95
	ds_write2_b64 v4, v[0:1], v[2:3] offset0:4 offset1:6
	v_cvt_pk_bf16_f32 v0, v64, v65
	v_cvt_pk_bf16_f32 v1, v66, v67
	v_cvt_pk_bf16_f32 v2, v68, v69
	v_cvt_pk_bf16_f32 v3, v70, v71
	v_add_u32_e32 v4, 0x4000, v4
	ds_write2_b64 v4, v[0:1], v[2:3] offset0:64 offset1:66
	v_cvt_pk_bf16_f32 v0, v72, v73
	v_cvt_pk_bf16_f32 v1, v74, v75
	v_cvt_pk_bf16_f32 v2, v76, v77
	v_cvt_pk_bf16_f32 v3, v78, v79
	v_lshl_add_u64 v[52:53], s[26:27], 0, v[168:169]
	ds_write2_b64 v4, v[0:1], v[2:3] offset0:68 offset1:70
	v_lshlrev_b64 v[0:1], 12, v[52:53]
	v_lshl_add_u64 v[0:1], s[24:25], 0, v[0:1]
	s_lshl_b32 s4, s61, 9
	s_mov_b32 s5, s27
	v_lshl_add_u64 v[0:1], v[0:1], 0, s[4:5]
	v_mov_b32_e32 v187, v171
	v_lshl_add_u64 v[16:17], v[0:1], 0, v[186:187]
	s_waitcnt lgkmcnt(0)
	s_barrier
; DI unsigned pk_bf16(float lo, float hi) { f32x2v v = {lo, hi}; bf16x2v b = __builtin_convertvector(v, bf16x2v); return __builtin_bit_cast(unsigned, b); }
; DI float bf_lo(unsigned u) { return __uint_as_float(u << 16); }
; DI float bf_hi(unsigned u) { return __uint_as_float(u & 0xffff0000u); }
; DI void phase5(const Params& p, char* smem) {
;     ...
; #pragma unroll
;       for (int hb = 0; hb < 2; ++hb) {
;         uint4 gav[4], gbv[4];
; #pragma unroll
;         for (int i = 0; i < 4; ++i) {
;           const size_t tok = (size_t)tokTile * 128 + r0 + 16 * (hb * 4 + i);
;           gav[i] = *(const uint4*)(p.pg + tok * 2048 + nt * 256 + ch * 8); gbv[i] = *(const uint4*)(p.pg + tok * 2048 + 1024 + nt * 256 + ch * 8);
;         }
; #pragma unroll
;         for (int i = 0; i < 4; ++i) {
;           const int row = r0 + 16 * (hb * 4 + i);
;           const size_t tok = (size_t)tokTile * 128 + row;
;           const uint4 u1 = *(const uint4*)(t1 + row * 528 + ch * 16), u2 = *(const uint4*)(t2 + row * 528 + ch * 16);
;           const uint4 ga = gav[i], gb = gbv[i];
;           uint4 o;
;           o.x = pk_bf16(bf_lo(ga.x) * bf_lo(u1.x) + bf_lo(gb.x) * bf_lo(u2.x), bf_hi(ga.x) * bf_hi(u1.x) + bf_hi(gb.x) * bf_hi(u2.x));
;           o.y = pk_bf16(bf_lo(ga.y) * bf_lo(u1.y) + bf_lo(gb.y) * bf_lo(u2.y), bf_hi(ga.y) * bf_hi(u1.y) + bf_hi(gb.y) * bf_hi(u2.y));
;           o.z = pk_bf16(bf_lo(ga.z) * bf_lo(u1.z) + bf_lo(gb.z) * bf_lo(u2.z), bf_hi(ga.z) * bf_hi(u1.z) + bf_hi(gb.z) * bf_hi(u2.z));
;           o.w = pk_bf16(bf_lo(ga.w) * bf_lo(u1.w) + bf_lo(gb.w) * bf_lo(u2.w), bf_hi(ga.w) * bf_hi(u1.w) + bf_hi(gb.w) * bf_hi(u2.w));
;           *(uint4*)(p.m + tok * DM + nt * 256 + ch * 8) = o;
;         }
	s_waitcnt vmcnt(0)
	s_mov_b32 s99, 0
	s_mov_b32 s98, s56
	v_lshl_add_u64 v[216:217], v[16:17], 0, s[98:99]
	global_load_dwordx4 v[96:99], v[216:217], off
	global_load_dwordx4 v[100:103], v[216:217], off offset:2048
	s_mov_b32 s98, s57
	v_lshl_add_u64 v[216:217], v[16:17], 0, s[98:99]
	global_load_dwordx4 v[104:107], v[216:217], off
	global_load_dwordx4 v[108:111], v[216:217], off offset:2048
	s_mov_b32 s98, s58
	v_lshl_add_u64 v[216:217], v[16:17], 0, s[98:99]
	global_load_dwordx4 v[112:115], v[216:217], off
	global_load_dwordx4 v[116:119], v[216:217], off offset:2048
	s_mov_b32 s98, s59
	v_lshl_add_u64 v[216:217], v[16:17], 0, s[98:99]
	global_load_dwordx4 v[120:123], v[216:217], off
	global_load_dwordx4 v[124:127], v[216:217], off offset:2048
	v_mov_b32_e32 v20, v188
	v_mov_b32_e32 v21, v189
	v_mov_b32_e32 v22, v190
	v_mov_b32_e32 v23, v191
	v_mov_b32_e32 v24, v192
	v_mov_b32_e32 v25, v193
	v_mov_b32_e32 v26, v194
	v_mov_b32_e32 v27, v195
	v_add_co_u32_e32 v0, vcc, s53, v16
	v_add_u32_e32 v18, v204, v205
	s_nop 0
	v_addc_co_u32_e32 v1, vcc, 0, v17, vcc
	v_mov_b32_e32 v28, v196
	v_mov_b32_e32 v29, v197
	v_mov_b32_e32 v30, v198
	v_mov_b32_e32 v31, v199
	v_mov_b32_e32 v32, v200
	v_mov_b32_e32 v33, v201
	v_mov_b32_e32 v34, v202
	v_mov_b32_e32 v35, v203
	v_add_co_u32_e32 v0, vcc, s54, v16
	s_add_i32 s60, s60, s95
	s_nop 0
	v_addc_co_u32_e32 v1, vcc, 0, v17, vcc
	v_mov_b32_e32 v12, v234
	v_mov_b32_e32 v13, v235
	v_mov_b32_e32 v14, v236
	v_mov_b32_e32 v15, v237
	v_mov_b32_e32 v8, v238
	v_mov_b32_e32 v9, v239
	v_mov_b32_e32 v10, v240
	v_mov_b32_e32 v11, v241
	v_add_co_u32_e32 v0, vcc, s55, v16
	ds_read_b128 v[36:39], v18
	s_nop 0
	v_addc_co_u32_e32 v1, vcc, 0, v17, vcc
	v_mov_b32_e32 v4, v242
	v_mov_b32_e32 v5, v243
	v_mov_b32_e32 v6, v244
	v_mov_b32_e32 v7, v245
	s_nop 0
	v_mov_b32_e32 v0, v246
	v_mov_b32_e32 v1, v247
	v_mov_b32_e32 v2, v248
	v_mov_b32_e32 v3, v249
	ds_read_b128 v[40:43], v206
	ds_read_b128 v[44:47], v18 offset:8448
	s_waitcnt lgkmcnt(2)
	v_lshlrev_b32_e32 v56, 16, v36
	v_and_b32_e32 v57, 0xffff0000, v36
	v_lshlrev_b32_e32 v36, 16, v37
	s_waitcnt lgkmcnt(1)
	v_lshlrev_b32_e32 v60, 16, v40
	v_and_b32_e32 v61, 0xffff0000, v40
	v_lshlrev_b32_e32 v40, 16, v41
	v_and_b32_e32 v41, 0xffff0000, v41
	v_and_b32_e32 v37, 0xffff0000, v37
	ds_read_b128 v[48:51], v206 offset:8448
	s_cmpk_lt_u32 s60, 0x100
	v_lshlrev_b32_e32 v54, 16, v20
	v_lshlrev_b32_e32 v58, 16, v24
	v_and_b32_e32 v59, 0xffff0000, v24
	v_and_b32_e32 v55, 0xffff0000, v20
	v_pk_mul_f32 v[58:59], v[58:59], v[60:61]
	v_lshlrev_b32_e32 v24, 16, v25
	v_pk_fma_f32 v[54:55], v[54:55], v[56:57], v[58:59]
	v_and_b32_e32 v25, 0xffff0000, v25
	v_cvt_pk_bf16_f32 v20, v54, v55
	v_lshlrev_b32_e32 v54, 16, v21
	v_and_b32_e32 v55, 0xffff0000, v21
	v_pk_mul_f32 v[24:25], v[24:25], v[40:41]
	v_lshlrev_b32_e32 v40, 16, v26
	v_pk_fma_f32 v[24:25], v[54:55], v[36:37], v[24:25]
	v_lshlrev_b32_e32 v54, 16, v42
	v_and_b32_e32 v41, 0xffff0000, v26
	v_and_b32_e32 v55, 0xffff0000, v42
	v_cvt_pk_bf16_f32 v21, v24, v25
	v_lshlrev_b32_e32 v24, 16, v22
	v_lshlrev_b32_e32 v36, 16, v38
	v_and_b32_e32 v25, 0xffff0000, v22
	v_and_b32_e32 v37, 0xffff0000, v38
	v_pk_mul_f32 v[40:41], v[40:41], v[54:55]
	v_lshlrev_b32_e32 v26, 16, v27
	v_pk_fma_f32 v[24:25], v[24:25], v[36:37], v[40:41]
	v_lshlrev_b32_e32 v36, 16, v39
	v_lshlrev_b32_e32 v38, 16, v43
	v_and_b32_e32 v37, 0xffff0000, v39
	v_and_b32_e32 v27, 0xffff0000, v27
	v_and_b32_e32 v39, 0xffff0000, v43
	v_cvt_pk_bf16_f32 v22, v24, v25
	v_lshlrev_b32_e32 v24, 16, v23
	v_and_b32_e32 v25, 0xffff0000, v23
	v_pk_mul_f32 v[26:27], v[26:27], v[38:39]
	v_lshlrev_b32_e32 v42, 16, v8
	v_pk_fma_f32 v[24:25], v[24:25], v[36:37], v[26:27]
	v_lshlrev_b32_e32 v26, 16, v32
	v_cvt_pk_bf16_f32 v23, v24, v25
	v_lshlrev_b64 v[24:25], 11, v[52:53]
	v_lshl_add_u64 v[24:25], s[18:19], 0, v[24:25]
	v_lshl_add_u64 v[24:25], v[24:25], 0, s[4:5]
	v_lshl_add_u64 v[24:25], v[24:25], 0, v[186:187]
	s_waitcnt lgkmcnt(0)
	v_lshlrev_b32_e32 v36, 16, v48
	v_and_b32_e32 v27, 0xffff0000, v32
	v_and_b32_e32 v37, 0xffff0000, v48
	global_store_dwordx4 v[24:25], v[20:23], off
	v_pk_mul_f32 v[26:27], v[26:27], v[36:37]
	v_lshlrev_b32_e32 v32, 16, v49
	v_lshlrev_b32_e32 v20, 16, v28
	v_lshlrev_b32_e32 v22, 16, v44
	v_and_b32_e32 v21, 0xffff0000, v28
	v_and_b32_e32 v23, 0xffff0000, v44
	v_pk_fma_f32 v[20:21], v[20:21], v[22:23], v[26:27]
	v_lshlrev_b32_e32 v22, 16, v29
	v_lshlrev_b32_e32 v28, 16, v33
	v_and_b32_e32 v23, 0xffff0000, v29
	v_and_b32_e32 v29, 0xffff0000, v33
	v_and_b32_e32 v33, 0xffff0000, v49
	v_lshlrev_b32_e32 v26, 16, v45
	v_and_b32_e32 v27, 0xffff0000, v45
	v_pk_mul_f32 v[28:29], v[28:29], v[32:33]
	v_lshlrev_b32_e32 v32, 16, v50
	v_pk_fma_f32 v[22:23], v[22:23], v[26:27], v[28:29]
	v_lshlrev_b32_e32 v28, 16, v34
	v_and_b32_e32 v29, 0xffff0000, v34
	v_and_b32_e32 v33, 0xffff0000, v50
	v_lshl_add_u64 v[24:25], s[26:27], 0, v[174:175]
	v_cvt_pk_bf16_f32 v20, v20, v21
	v_cvt_pk_bf16_f32 v21, v22, v23
	v_lshlrev_b32_e32 v22, 16, v30
	v_lshlrev_b32_e32 v26, 16, v46
	v_and_b32_e32 v23, 0xffff0000, v30
	v_and_b32_e32 v27, 0xffff0000, v46
	v_pk_mul_f32 v[28:29], v[28:29], v[32:33]
	v_lshlrev_b32_e32 v30, 16, v35
	v_pk_fma_f32 v[22:23], v[22:23], v[26:27], v[28:29]
	v_lshlrev_b32_e32 v26, 16, v31
	v_lshlrev_b32_e32 v32, 16, v51
	v_and_b32_e32 v27, 0xffff0000, v31
	v_and_b32_e32 v31, 0xffff0000, v35
	v_and_b32_e32 v33, 0xffff0000, v51
	v_lshlrev_b64 v[24:25], 11, v[24:25]
	v_lshlrev_b32_e32 v28, 16, v47
	v_and_b32_e32 v29, 0xffff0000, v47
	v_pk_mul_f32 v[30:31], v[30:31], v[32:33]
	v_lshl_add_u64 v[24:25], s[18:19], 0, v[24:25]
	v_pk_fma_f32 v[26:27], v[26:27], v[28:29], v[30:31]
	v_lshl_add_u64 v[24:25], v[24:25], 0, s[4:5]
	v_cvt_pk_bf16_f32 v22, v22, v23
	v_cvt_pk_bf16_f32 v23, v26, v27
	v_lshl_add_u64 v[24:25], v[24:25], 0, v[186:187]
	global_store_dwordx4 v[24:25], v[20:23], off
	ds_read_b128 v[24:27], v206 offset:16896
	ds_read_b128 v[32:35], v206 offset:25344
	ds_read_b128 v[20:23], v18 offset:16896
	ds_read_b128 v[28:31], v18 offset:25344
	v_and_b32_e32 v43, 0xffff0000, v8
	s_waitcnt lgkmcnt(3)
; DI unsigned pk_bf16(float lo, float hi) { f32x2v v = {lo, hi}; bf16x2v b = __builtin_convertvector(v, bf16x2v); return __builtin_bit_cast(unsigned, b); }
; DI float bf_lo(unsigned u) { return __uint_as_float(u << 16); }
; DI float bf_hi(unsigned u) { return __uint_as_float(u & 0xffff0000u); }
; DI void phase5(const Params& p, char* smem) {
;     ...
; #pragma unroll
;       for (int hb = 0; hb < 2; ++hb) {
;         uint4 gav[4], gbv[4];
; #pragma unroll
;         for (int i = 0; i < 4; ++i) {
;           const size_t tok = (size_t)tokTile * 128 + r0 + 16 * (hb * 4 + i);
;           gav[i] = *(const uint4*)(p.pg + tok * 2048 + nt * 256 + ch * 8); gbv[i] = *(const uint4*)(p.pg + tok * 2048 + 1024 + nt * 256 + ch * 8);
;         }
; #pragma unroll
;         for (int i = 0; i < 4; ++i) {
;           const int row = r0 + 16 * (hb * 4 + i);
;           const size_t tok = (size_t)tokTile * 128 + row;
;           const uint4 u1 = *(const uint4*)(t1 + row * 528 + ch * 16), u2 = *(const uint4*)(t2 + row * 528 + ch * 16);
;           const uint4 ga = gav[i], gb = gbv[i];
;           uint4 o;
;           o.x = pk_bf16(bf_lo(ga.x) * bf_lo(u1.x) + bf_lo(gb.x) * bf_lo(u2.x), bf_hi(ga.x) * bf_hi(u1.x) + bf_hi(gb.x) * bf_hi(u2.x));
;           o.y = pk_bf16(bf_lo(ga.y) * bf_lo(u1.y) + bf_lo(gb.y) * bf_lo(u2.y), bf_hi(ga.y) * bf_hi(u1.y) + bf_hi(gb.y) * bf_hi(u2.y));
;           o.z = pk_bf16(bf_lo(ga.z) * bf_lo(u1.z) + bf_lo(gb.z) * bf_lo(u2.z), bf_hi(ga.z) * bf_hi(u1.z) + bf_hi(gb.z) * bf_hi(u2.z));
;           o.w = pk_bf16(bf_lo(ga.w) * bf_lo(u1.w) + bf_lo(gb.w) * bf_lo(u2.w), bf_hi(ga.w) * bf_hi(u1.w) + bf_hi(gb.w) * bf_hi(u2.w));
;           *(uint4*)(p.m + tok * DM + nt * 256 + ch * 8) = o;
;         }
	v_lshlrev_b32_e32 v44, 16, v24
	v_and_b32_e32 v45, 0xffff0000, v24
	v_lshlrev_b32_e32 v38, 16, v12
	s_waitcnt lgkmcnt(1)
	v_lshlrev_b32_e32 v40, 16, v20
	v_and_b32_e32 v39, 0xffff0000, v12
	v_and_b32_e32 v41, 0xffff0000, v20
	v_pk_mul_f32 v[42:43], v[42:43], v[44:45]
	v_lshlrev_b32_e32 v24, 16, v25
	v_pk_fma_f32 v[38:39], v[38:39], v[40:41], v[42:43]
	v_and_b32_e32 v25, 0xffff0000, v25
	v_cvt_pk_bf16_f32 v8, v38, v39
	v_lshlrev_b32_e32 v38, 16, v9
	v_and_b32_e32 v39, 0xffff0000, v9
	v_lshlrev_b32_e32 v12, 16, v13
	v_lshlrev_b32_e32 v20, 16, v21
	v_and_b32_e32 v13, 0xffff0000, v13
	v_and_b32_e32 v21, 0xffff0000, v21
	v_pk_mul_f32 v[24:25], v[38:39], v[24:25]
	v_lshlrev_b32_e32 v38, 16, v26
	v_pk_fma_f32 v[12:13], v[12:13], v[20:21], v[24:25]
	v_lshlrev_b32_e32 v24, 16, v10
	v_and_b32_e32 v25, 0xffff0000, v10
	v_and_b32_e32 v39, 0xffff0000, v26
	v_cvt_pk_bf16_f32 v9, v12, v13
	v_lshlrev_b32_e32 v12, 16, v14
	v_lshlrev_b32_e32 v20, 16, v22
	v_and_b32_e32 v13, 0xffff0000, v14
	v_and_b32_e32 v21, 0xffff0000, v22
	v_pk_mul_f32 v[24:25], v[24:25], v[38:39]
	v_lshlrev_b32_e32 v14, 16, v23
	v_pk_fma_f32 v[12:13], v[12:13], v[20:21], v[24:25]
	v_lshlrev_b32_e32 v20, 16, v11
	v_cvt_pk_bf16_f32 v10, v12, v13
	v_lshlrev_b32_e32 v12, 16, v15
	v_lshlrev_b32_e32 v22, 16, v27
	v_and_b32_e32 v13, 0xffff0000, v15
	v_and_b32_e32 v15, 0xffff0000, v23
	v_and_b32_e32 v21, 0xffff0000, v11
	v_and_b32_e32 v23, 0xffff0000, v27
	v_pk_mul_f32 v[20:21], v[20:21], v[22:23]
	v_lshl_add_u64 v[36:37], s[26:27], 0, v[176:177]
	v_pk_fma_f32 v[12:13], v[12:13], v[14:15], v[20:21]
	v_lshlrev_b32_e32 v14, 16, v0
	v_cvt_pk_bf16_f32 v11, v12, v13
	v_lshlrev_b64 v[12:13], 11, v[36:37]
	v_lshl_add_u64 v[12:13], s[18:19], 0, v[12:13]
	v_lshl_add_u64 v[12:13], v[12:13], 0, s[4:5]
	v_lshl_add_u64 v[12:13], v[12:13], 0, v[186:187]
	v_lshlrev_b32_e32 v20, 16, v32
	v_and_b32_e32 v15, 0xffff0000, v0
	v_and_b32_e32 v21, 0xffff0000, v32
	global_store_dwordx4 v[12:13], v[8:11], off
	s_waitcnt lgkmcnt(0)
	v_lshlrev_b32_e32 v12, 16, v28
	v_and_b32_e32 v13, 0xffff0000, v28
	v_lshlrev_b32_e32 v10, 16, v4
	v_and_b32_e32 v11, 0xffff0000, v4
	v_pk_mul_f32 v[14:15], v[14:15], v[20:21]
	v_lshlrev_b32_e32 v4, 16, v5
	v_pk_fma_f32 v[10:11], v[10:11], v[12:13], v[14:15]
	v_lshlrev_b32_e32 v12, 16, v1
	v_lshlrev_b32_e32 v14, 16, v33
	v_and_b32_e32 v13, 0xffff0000, v1
	v_and_b32_e32 v15, 0xffff0000, v33
	v_cvt_pk_bf16_f32 v0, v10, v11
	v_lshlrev_b32_e32 v10, 16, v29
	v_and_b32_e32 v5, 0xffff0000, v5
	v_and_b32_e32 v11, 0xffff0000, v29
	v_pk_mul_f32 v[12:13], v[12:13], v[14:15]
	v_lshlrev_b32_e32 v14, 16, v34
	v_pk_fma_f32 v[4:5], v[4:5], v[10:11], v[12:13]
	v_lshlrev_b32_e32 v12, 16, v2
	v_and_b32_e32 v13, 0xffff0000, v2
	v_and_b32_e32 v15, 0xffff0000, v34
	v_cvt_pk_bf16_f32 v1, v4, v5
	v_lshlrev_b32_e32 v4, 16, v6
	v_lshlrev_b32_e32 v10, 16, v30
	v_and_b32_e32 v5, 0xffff0000, v6
	v_and_b32_e32 v11, 0xffff0000, v30
	v_pk_mul_f32 v[12:13], v[12:13], v[14:15]
	v_lshlrev_b32_e32 v6, 16, v31
	v_pk_fma_f32 v[4:5], v[4:5], v[10:11], v[12:13]
	v_lshlrev_b32_e32 v10, 16, v3
	v_lshlrev_b32_e32 v12, 16, v35
	v_and_b32_e32 v11, 0xffff0000, v3
	v_and_b32_e32 v13, 0xffff0000, v35
	v_cvt_pk_bf16_f32 v2, v4, v5
	v_lshlrev_b32_e32 v4, 16, v7
	v_and_b32_e32 v5, 0xffff0000, v7
	v_and_b32_e32 v7, 0xffff0000, v31
	v_pk_mul_f32 v[10:11], v[10:11], v[12:13]
	v_lshl_add_u64 v[8:9], s[26:27], 0, v[178:179]
	v_pk_fma_f32 v[4:5], v[4:5], v[6:7], v[10:11]
	s_nop 0
	v_cvt_pk_bf16_f32 v3, v4, v5
	v_lshlrev_b64 v[4:5], 11, v[8:9]
	v_lshl_add_u64 v[4:5], s[18:19], 0, v[4:5]
	v_lshl_add_u64 v[4:5], v[4:5], 0, s[4:5]
	v_lshl_add_u64 v[4:5], v[4:5], 0, v[186:187]
	global_store_dwordx4 v[4:5], v[0:3], off
	s_nop 1
	v_add_co_u32_e32 v0, vcc, s56, v16
	s_nop 1
	v_addc_co_u32_e32 v1, vcc, 0, v17, vcc
	s_waitcnt vmcnt(4)
	v_mov_b32_e32 v20, v96
	v_mov_b32_e32 v21, v97
	v_mov_b32_e32 v22, v98
	v_mov_b32_e32 v23, v99
	v_mov_b32_e32 v24, v100
	v_mov_b32_e32 v25, v101
	v_mov_b32_e32 v26, v102
	v_mov_b32_e32 v27, v103
	v_add_co_u32_e32 v0, vcc, s57, v16
	v_lshlrev_b32_e32 v52, 16, v20
	v_addc_co_u32_e32 v1, vcc, 0, v17, vcc
	v_mov_b32_e32 v28, v104
	v_mov_b32_e32 v29, v105
	v_mov_b32_e32 v30, v106
	v_mov_b32_e32 v31, v107
	v_mov_b32_e32 v32, v108
	v_mov_b32_e32 v33, v109
	v_mov_b32_e32 v34, v110
	v_mov_b32_e32 v35, v111
	v_add_co_u32_e32 v0, vcc, s58, v16
	v_lshlrev_b32_e32 v56, 16, v24
	v_addc_co_u32_e32 v1, vcc, 0, v17, vcc
	v_mov_b32_e32 v12, v112
	v_mov_b32_e32 v13, v113
	v_mov_b32_e32 v14, v114
	v_mov_b32_e32 v15, v115
	v_mov_b32_e32 v8, v116
	v_mov_b32_e32 v9, v117
	v_mov_b32_e32 v10, v118
	v_mov_b32_e32 v11, v119
	v_add_co_u32_e32 v0, vcc, s59, v16
	v_and_b32_e32 v57, 0xffff0000, v24
	s_nop 0
	v_addc_co_u32_e32 v1, vcc, 0, v17, vcc
	v_mov_b32_e32 v4, v120
	v_mov_b32_e32 v5, v121
	v_mov_b32_e32 v6, v122
	v_mov_b32_e32 v7, v123
	s_nop 0
	v_mov_b32_e32 v0, v124
	v_mov_b32_e32 v1, v125
	v_mov_b32_e32 v2, v126
	v_mov_b32_e32 v3, v127
	ds_read_b128 v[40:43], v206 offset:33792
	ds_read_b128 v[48:51], v206 offset:42240
	ds_read_b128 v[36:39], v18 offset:33792
	ds_read_b128 v[44:47], v18 offset:42240
	v_and_b32_e32 v53, 0xffff0000, v20
	s_waitcnt lgkmcnt(3)
	v_lshlrev_b32_e32 v58, 16, v40
	v_and_b32_e32 v59, 0xffff0000, v40
	s_waitcnt lgkmcnt(1)
; DI unsigned pk_bf16(float lo, float hi) { f32x2v v = {lo, hi}; bf16x2v b = __builtin_convertvector(v, bf16x2v); return __builtin_bit_cast(unsigned, b); }
; DI float bf_lo(unsigned u) { return __uint_as_float(u << 16); }
; DI float bf_hi(unsigned u) { return __uint_as_float(u & 0xffff0000u); }
; DI void phase5(const Params& p, char* smem) {
;     ...
; #pragma unroll
;       for (int hb = 0; hb < 2; ++hb) {
;         uint4 gav[4], gbv[4];
; #pragma unroll
;         for (int i = 0; i < 4; ++i) {
;           const size_t tok = (size_t)tokTile * 128 + r0 + 16 * (hb * 4 + i);
;           gav[i] = *(const uint4*)(p.pg + tok * 2048 + nt * 256 + ch * 8); gbv[i] = *(const uint4*)(p.pg + tok * 2048 + 1024 + nt * 256 + ch * 8);
;         }
; #pragma unroll
;         for (int i = 0; i < 4; ++i) {
;           const int row = r0 + 16 * (hb * 4 + i);
;           const size_t tok = (size_t)tokTile * 128 + row;
;           const uint4 u1 = *(const uint4*)(t1 + row * 528 + ch * 16), u2 = *(const uint4*)(t2 + row * 528 + ch * 16);
;           const uint4 ga = gav[i], gb = gbv[i];
;           uint4 o;
;           o.x = pk_bf16(bf_lo(ga.x) * bf_lo(u1.x) + bf_lo(gb.x) * bf_lo(u2.x), bf_hi(ga.x) * bf_hi(u1.x) + bf_hi(gb.x) * bf_hi(u2.x));
;           o.y = pk_bf16(bf_lo(ga.y) * bf_lo(u1.y) + bf_lo(gb.y) * bf_lo(u2.y), bf_hi(ga.y) * bf_hi(u1.y) + bf_hi(gb.y) * bf_hi(u2.y));
;           o.z = pk_bf16(bf_lo(ga.z) * bf_lo(u1.z) + bf_lo(gb.z) * bf_lo(u2.z), bf_hi(ga.z) * bf_hi(u1.z) + bf_hi(gb.z) * bf_hi(u2.z));
;           o.w = pk_bf16(bf_lo(ga.w) * bf_lo(u1.w) + bf_lo(gb.w) * bf_lo(u2.w), bf_hi(ga.w) * bf_hi(u1.w) + bf_hi(gb.w) * bf_hi(u2.w));
;           *(uint4*)(p.m + tok * DM + nt * 256 + ch * 8) = o;
;         }
	v_lshlrev_b32_e32 v54, 16, v36
	v_and_b32_e32 v55, 0xffff0000, v36
	v_pk_mul_f32 v[56:57], v[56:57], v[58:59]
	v_lshlrev_b32_e32 v24, 16, v25
	v_pk_fma_f32 v[52:53], v[52:53], v[54:55], v[56:57]
	v_lshlrev_b32_e32 v40, 16, v41
	v_and_b32_e32 v25, 0xffff0000, v25
	v_and_b32_e32 v41, 0xffff0000, v41
	v_cvt_pk_bf16_f32 v20, v52, v53
	v_lshlrev_b32_e32 v52, 16, v21
	v_lshlrev_b32_e32 v36, 16, v37
	v_and_b32_e32 v53, 0xffff0000, v21
	v_and_b32_e32 v37, 0xffff0000, v37
	v_pk_mul_f32 v[24:25], v[24:25], v[40:41]
	v_lshlrev_b32_e32 v40, 16, v26
	v_pk_fma_f32 v[24:25], v[52:53], v[36:37], v[24:25]
	v_lshlrev_b32_e32 v52, 16, v42
	v_and_b32_e32 v41, 0xffff0000, v26
	v_and_b32_e32 v53, 0xffff0000, v42
	v_lshl_add_u64 v[16:17], s[26:27], 0, v[172:173]
	v_cvt_pk_bf16_f32 v21, v24, v25
	v_lshlrev_b32_e32 v24, 16, v22
	v_lshlrev_b32_e32 v36, 16, v38
	v_and_b32_e32 v25, 0xffff0000, v22
	v_and_b32_e32 v37, 0xffff0000, v38
	v_pk_mul_f32 v[40:41], v[40:41], v[52:53]
	v_lshlrev_b32_e32 v26, 16, v27
	v_pk_fma_f32 v[24:25], v[24:25], v[36:37], v[40:41]
	v_lshlrev_b32_e32 v36, 16, v39
	v_lshlrev_b32_e32 v38, 16, v43
	v_and_b32_e32 v37, 0xffff0000, v39
	v_and_b32_e32 v27, 0xffff0000, v27
	v_and_b32_e32 v39, 0xffff0000, v43
	v_lshlrev_b64 v[16:17], 11, v[16:17]
	v_cvt_pk_bf16_f32 v22, v24, v25
	v_lshlrev_b32_e32 v24, 16, v23
	v_and_b32_e32 v25, 0xffff0000, v23
	v_pk_mul_f32 v[26:27], v[26:27], v[38:39]
	v_lshl_add_u64 v[16:17], s[18:19], 0, v[16:17]
	v_pk_fma_f32 v[24:25], v[24:25], v[36:37], v[26:27]
	v_lshl_add_u64 v[16:17], v[16:17], 0, s[4:5]
	v_cvt_pk_bf16_f32 v23, v24, v25
	v_lshl_add_u64 v[16:17], v[16:17], 0, v[186:187]
	v_lshlrev_b32_e32 v26, 16, v48
	v_and_b32_e32 v27, 0xffff0000, v48
	global_store_dwordx4 v[16:17], v[20:23], off
	v_lshl_add_u64 v[16:17], s[26:27], 0, v[180:181]
	v_lshlrev_b64 v[16:17], 11, v[16:17]
	s_waitcnt lgkmcnt(0)
	v_lshlrev_b32_e32 v22, 16, v44
	v_and_b32_e32 v23, 0xffff0000, v44
	v_lshl_add_u64 v[16:17], s[18:19], 0, v[16:17]
	v_lshl_add_u64 v[16:17], v[16:17], 0, s[4:5]
	v_lshl_add_u64 v[16:17], v[16:17], 0, v[186:187]
	v_lshlrev_b32_e32 v20, 16, v28
	v_lshlrev_b32_e32 v24, 16, v32
	v_and_b32_e32 v25, 0xffff0000, v32
	v_and_b32_e32 v21, 0xffff0000, v28
	v_pk_mul_f32 v[24:25], v[24:25], v[26:27]
	v_lshlrev_b32_e32 v26, 16, v33
	v_pk_fma_f32 v[20:21], v[20:21], v[22:23], v[24:25]
	v_lshlrev_b32_e32 v22, 16, v29
	v_lshlrev_b32_e32 v28, 16, v49
	v_and_b32_e32 v23, 0xffff0000, v29
	v_and_b32_e32 v27, 0xffff0000, v33
	v_and_b32_e32 v29, 0xffff0000, v49
	v_lshlrev_b32_e32 v24, 16, v45
	v_and_b32_e32 v25, 0xffff0000, v45
	v_pk_mul_f32 v[26:27], v[26:27], v[28:29]
	v_lshlrev_b32_e32 v28, 16, v50
	v_pk_fma_f32 v[22:23], v[22:23], v[24:25], v[26:27]
	v_lshlrev_b32_e32 v26, 16, v34
	v_and_b32_e32 v27, 0xffff0000, v34
	v_and_b32_e32 v29, 0xffff0000, v50
	v_cvt_pk_bf16_f32 v20, v20, v21
	v_cvt_pk_bf16_f32 v21, v22, v23
	v_lshlrev_b32_e32 v22, 16, v30
	v_lshlrev_b32_e32 v24, 16, v46
	v_and_b32_e32 v23, 0xffff0000, v30
	v_and_b32_e32 v25, 0xffff0000, v46
	v_pk_mul_f32 v[26:27], v[26:27], v[28:29]
	v_lshlrev_b32_e32 v28, 16, v35
	v_pk_fma_f32 v[22:23], v[22:23], v[24:25], v[26:27]
	v_lshlrev_b32_e32 v24, 16, v31
	v_lshlrev_b32_e32 v30, 16, v51
	v_and_b32_e32 v25, 0xffff0000, v31
	v_and_b32_e32 v29, 0xffff0000, v35
	v_and_b32_e32 v31, 0xffff0000, v51
	v_lshlrev_b32_e32 v26, 16, v47
	v_and_b32_e32 v27, 0xffff0000, v47
	v_pk_mul_f32 v[28:29], v[28:29], v[30:31]
	v_cvt_pk_bf16_f32 v22, v22, v23
	v_pk_fma_f32 v[24:25], v[24:25], v[26:27], v[28:29]
	v_lshlrev_b32_e32 v38, 16, v8
	v_cvt_pk_bf16_f32 v23, v24, v25
	global_store_dwordx4 v[16:17], v[20:23], off
	ds_read_b128 v[20:23], v18 offset:50688
	ds_read_b128 v[24:27], v206 offset:50688
	v_and_b32_e32 v39, 0xffff0000, v8
	v_lshlrev_b32_e32 v34, 16, v12
	v_and_b32_e32 v35, 0xffff0000, v12
	s_waitcnt lgkmcnt(1)
; DI unsigned pk_bf16(float lo, float hi) { f32x2v v = {lo, hi}; bf16x2v b = __builtin_convertvector(v, bf16x2v); return __builtin_bit_cast(unsigned, b); }
; DI float bf_lo(unsigned u) { return __uint_as_float(u << 16); }
; DI float bf_hi(unsigned u) { return __uint_as_float(u & 0xffff0000u); }
; DI void lds_sync() { wait_lgkm0(); bar_(); }
; DI void phase5(const Params& p, char* smem) {
;     ...
; #pragma unroll
;       for (int hb = 0; hb < 2; ++hb) {
;         uint4 gav[4], gbv[4];
; #pragma unroll
;         for (int i = 0; i < 4; ++i) {
;           const size_t tok = (size_t)tokTile * 128 + r0 + 16 * (hb * 4 + i);
;           gav[i] = *(const uint4*)(p.pg + tok * 2048 + nt * 256 + ch * 8); gbv[i] = *(const uint4*)(p.pg + tok * 2048 + 1024 + nt * 256 + ch * 8);
;         }
; #pragma unroll
;         for (int i = 0; i < 4; ++i) {
;           const int row = r0 + 16 * (hb * 4 + i);
;           const size_t tok = (size_t)tokTile * 128 + row;
;           const uint4 u1 = *(const uint4*)(t1 + row * 528 + ch * 16), u2 = *(const uint4*)(t2 + row * 528 + ch * 16);
;           const uint4 ga = gav[i], gb = gbv[i];
;           uint4 o;
;           o.x = pk_bf16(bf_lo(ga.x) * bf_lo(u1.x) + bf_lo(gb.x) * bf_lo(u2.x), bf_hi(ga.x) * bf_hi(u1.x) + bf_hi(gb.x) * bf_hi(u2.x));
;           o.y = pk_bf16(bf_lo(ga.y) * bf_lo(u1.y) + bf_lo(gb.y) * bf_lo(u2.y), bf_hi(ga.y) * bf_hi(u1.y) + bf_hi(gb.y) * bf_hi(u2.y));
;           o.z = pk_bf16(bf_lo(ga.z) * bf_lo(u1.z) + bf_lo(gb.z) * bf_lo(u2.z), bf_hi(ga.z) * bf_hi(u1.z) + bf_hi(gb.z) * bf_hi(u2.z));
;           o.w = pk_bf16(bf_lo(ga.w) * bf_lo(u1.w) + bf_lo(gb.w) * bf_lo(u2.w), bf_hi(ga.w) * bf_hi(u1.w) + bf_hi(gb.w) * bf_hi(u2.w));
;           *(uint4*)(p.m + tok * DM + nt * 256 + ch * 8) = o;
;         }
;       }
;       lds_sync();
;     }
;   }
	v_lshlrev_b32_e32 v36, 16, v20
	s_waitcnt lgkmcnt(0)
	v_lshlrev_b32_e32 v40, 16, v24
	v_and_b32_e32 v41, 0xffff0000, v24
	v_and_b32_e32 v37, 0xffff0000, v20
	v_pk_mul_f32 v[38:39], v[38:39], v[40:41]
	v_lshlrev_b32_e32 v24, 16, v25
	v_pk_fma_f32 v[34:35], v[34:35], v[36:37], v[38:39]
	v_and_b32_e32 v25, 0xffff0000, v25
	v_cvt_pk_bf16_f32 v8, v34, v35
	v_lshlrev_b32_e32 v34, 16, v9
	v_and_b32_e32 v35, 0xffff0000, v9
	v_lshlrev_b32_e32 v12, 16, v13
	v_lshlrev_b32_e32 v20, 16, v21
	v_and_b32_e32 v13, 0xffff0000, v13
	v_and_b32_e32 v21, 0xffff0000, v21
	v_pk_mul_f32 v[24:25], v[34:35], v[24:25]
	v_lshlrev_b32_e32 v34, 16, v26
	v_pk_fma_f32 v[12:13], v[12:13], v[20:21], v[24:25]
	v_lshlrev_b32_e32 v24, 16, v10
	v_and_b32_e32 v25, 0xffff0000, v10
	v_and_b32_e32 v35, 0xffff0000, v26
	v_cvt_pk_bf16_f32 v9, v12, v13
	v_lshlrev_b32_e32 v12, 16, v14
	v_lshlrev_b32_e32 v20, 16, v22
	v_and_b32_e32 v13, 0xffff0000, v14
	v_and_b32_e32 v21, 0xffff0000, v22
	v_pk_mul_f32 v[24:25], v[24:25], v[34:35]
	v_lshlrev_b32_e32 v14, 16, v23
	v_pk_fma_f32 v[12:13], v[12:13], v[20:21], v[24:25]
	v_lshlrev_b32_e32 v20, 16, v11
	v_cvt_pk_bf16_f32 v10, v12, v13
	v_lshlrev_b32_e32 v12, 16, v15
	v_lshlrev_b32_e32 v22, 16, v27
	v_and_b32_e32 v13, 0xffff0000, v15
	v_and_b32_e32 v15, 0xffff0000, v23
	v_and_b32_e32 v21, 0xffff0000, v11
	v_and_b32_e32 v23, 0xffff0000, v27
	ds_read_b128 v[16:19], v18 offset:59136
	ds_read_b128 v[28:31], v206 offset:59136
	v_pk_mul_f32 v[20:21], v[20:21], v[22:23]
	v_lshl_add_u64 v[32:33], s[26:27], 0, v[182:183]
	v_pk_fma_f32 v[12:13], v[12:13], v[14:15], v[20:21]
	v_lshlrev_b32_e32 v14, 16, v0
	v_cvt_pk_bf16_f32 v11, v12, v13
	v_lshlrev_b64 v[12:13], 11, v[32:33]
	v_lshl_add_u64 v[12:13], s[18:19], 0, v[12:13]
	v_lshl_add_u64 v[12:13], v[12:13], 0, s[4:5]
	v_lshl_add_u64 v[12:13], v[12:13], 0, v[186:187]
	s_waitcnt lgkmcnt(0)
	v_lshlrev_b32_e32 v20, 16, v28
	v_and_b32_e32 v15, 0xffff0000, v0
	v_and_b32_e32 v21, 0xffff0000, v28
	global_store_dwordx4 v[12:13], v[8:11], off
	v_lshlrev_b32_e32 v12, 16, v16
	v_and_b32_e32 v13, 0xffff0000, v16
	v_lshlrev_b32_e32 v10, 16, v4
	v_and_b32_e32 v11, 0xffff0000, v4
	v_pk_mul_f32 v[14:15], v[14:15], v[20:21]
	v_lshlrev_b32_e32 v4, 16, v5
	v_pk_fma_f32 v[10:11], v[10:11], v[12:13], v[14:15]
	v_lshlrev_b32_e32 v12, 16, v1
	v_lshlrev_b32_e32 v14, 16, v29
	v_and_b32_e32 v13, 0xffff0000, v1
	v_and_b32_e32 v15, 0xffff0000, v29
	v_cvt_pk_bf16_f32 v0, v10, v11
	v_lshlrev_b32_e32 v10, 16, v17
	v_and_b32_e32 v5, 0xffff0000, v5
	v_and_b32_e32 v11, 0xffff0000, v17
	v_pk_mul_f32 v[12:13], v[12:13], v[14:15]
	v_lshlrev_b32_e32 v14, 16, v30
	v_pk_fma_f32 v[4:5], v[4:5], v[10:11], v[12:13]
	v_lshlrev_b32_e32 v12, 16, v2
	v_and_b32_e32 v13, 0xffff0000, v2
	v_and_b32_e32 v15, 0xffff0000, v30
	v_cvt_pk_bf16_f32 v1, v4, v5
	v_lshlrev_b32_e32 v4, 16, v6
	v_lshlrev_b32_e32 v10, 16, v18
	v_and_b32_e32 v5, 0xffff0000, v6
	v_and_b32_e32 v11, 0xffff0000, v18
	v_pk_mul_f32 v[12:13], v[12:13], v[14:15]
	v_lshlrev_b32_e32 v6, 16, v19
	v_pk_fma_f32 v[4:5], v[4:5], v[10:11], v[12:13]
	v_lshlrev_b32_e32 v10, 16, v3
	v_lshlrev_b32_e32 v12, 16, v31
	v_and_b32_e32 v11, 0xffff0000, v3
	v_and_b32_e32 v13, 0xffff0000, v31
	v_cvt_pk_bf16_f32 v2, v4, v5
	v_lshlrev_b32_e32 v4, 16, v7
	v_and_b32_e32 v5, 0xffff0000, v7
	v_and_b32_e32 v7, 0xffff0000, v19
	v_pk_mul_f32 v[10:11], v[10:11], v[12:13]
	v_lshl_add_u64 v[8:9], s[26:27], 0, v[184:185]
	v_pk_fma_f32 v[4:5], v[4:5], v[6:7], v[10:11]
	s_nop 0
	v_cvt_pk_bf16_f32 v3, v4, v5
	v_lshlrev_b64 v[4:5], 11, v[8:9]
	v_lshl_add_u64 v[4:5], s[18:19], 0, v[4:5]
	v_lshl_add_u64 v[4:5], v[4:5], 0, s[4:5]
	v_lshl_add_u64 v[4:5], v[4:5], 0, v[186:187]
	global_store_dwordx4 v[4:5], v[0:3], off
	s_waitcnt lgkmcnt(0)
	s_barrier
	s_cbranch_scc0 .LBB0_882
